# att22 = att14 + down-proj fused-norm epilogue: the 8 SS[row] (sc1) loads issued together behind the panel sync with counted waits, instead of load-wait(vmcnt 0)-store rounds (8 serial round trips + st
# baseline (speedup 1.0000x reference)
.LBB0_925:
	global_load_dword v242, v[112:113], off sc1
	global_load_dword v243, v[176:177], off sc1
	global_load_dword v247, v[168:169], off sc1
	global_load_dword v248, v[160:161], off sc1
	global_load_dword v249, v[112:113], off offset:512 sc1
	global_load_dword v250, v[112:113], off offset:576 sc1
	global_load_dword v251, v[112:113], off offset:640 sc1
	global_load_dword v252, v[112:113], off offset:704 sc1
	v_lshlrev_b64 v[146:147], 12, v[216:217]
	v_lshl_add_u64 v[146:147], s[20:21], 0, v[146:147]
	s_and_b64 vcc, exec, s[6:7]
	s_mov_b64 s[0:1], -1
	s_waitcnt vmcnt(7)
	v_fmamk_f32 v144, v242, 0x3a800000, v226
	v_rsq_f32_e32 v148, v144
	v_lshlrev_b64 v[144:145], 2, v[214:215]
	v_lshl_add_u64 v[150:151], v[146:147], 0, v[144:145]
	v_pk_mul_f32 v[146:147], v[218:219], v[148:149] op_sel_hi:[1,0]
	v_pk_mul_f32 v[126:127], v[126:127], v[148:149] op_sel_hi:[1,0]
	v_pk_mul_f32 v[124:125], v[124:125], v[148:149] op_sel_hi:[1,0]
	v_pk_mul_f32 v[122:123], v[122:123], v[148:149] op_sel_hi:[1,0]
	v_pk_mul_f32 v[152:153], v[120:121], v[148:149] op_sel_hi:[1,0]
	v_pk_mul_f32 v[154:155], v[118:119], v[148:149] op_sel_hi:[1,0]
	v_pk_mul_f32 v[156:157], v[116:117], v[148:149] op_sel_hi:[1,0]
	v_pk_mul_f32 v[148:149], v[114:115], v[148:149] op_sel_hi:[1,0]
	v_pk_mul_f32 v[116:117], v[6:7], v[126:127]
	v_pk_mul_f32 v[114:115], v[4:5], v[146:147]
	v_pk_mul_f32 v[120:121], v[2:3], v[122:123]
	v_pk_mul_f32 v[118:119], v[0:1], v[124:125]
	v_pk_mul_f32 v[124:125], v[14:15], v[154:155]
	v_pk_mul_f32 v[122:123], v[12:13], v[152:153]
	v_pk_mul_f32 v[148:149], v[10:11], v[148:149]
	v_pk_mul_f32 v[146:147], v[8:9], v[156:157]
	global_store_dwordx4 v[150:151], v[114:117], off
	global_store_dwordx4 v[150:151], v[118:121], off offset:16
	global_store_dwordx4 v[150:151], v[122:125], off offset:512
	global_store_dwordx4 v[150:151], v[146:149], off offset:528
	v_lshlrev_b64 v[116:117], 12, v[212:213]
	v_lshl_add_u64 v[116:117], s[20:21], 0, v[116:117]
	v_lshl_add_u64 v[116:117], v[116:117], 0, v[144:145]
	s_waitcnt vmcnt(10)
	v_fmamk_f32 v114, v243, 0x3a800000, v226
	v_rsq_f32_e32 v114, v114
	s_nop 0
	v_pk_mul_f32 v[108:109], v[108:109], v[114:115] op_sel_hi:[1,0]
	v_pk_mul_f32 v[110:111], v[110:111], v[114:115] op_sel_hi:[1,0]
	v_pk_mul_f32 v[104:105], v[104:105], v[114:115] op_sel_hi:[1,0]
	v_pk_mul_f32 v[106:107], v[106:107], v[114:115] op_sel_hi:[1,0]
	v_pk_mul_f32 v[118:119], v[100:101], v[114:115] op_sel_hi:[1,0]
	v_pk_mul_f32 v[120:121], v[102:103], v[114:115] op_sel_hi:[1,0]
	v_pk_mul_f32 v[122:123], v[96:97], v[114:115] op_sel_hi:[1,0]
	v_pk_mul_f32 v[114:115], v[98:99], v[114:115] op_sel_hi:[1,0]
	v_pk_mul_f32 v[98:99], v[6:7], v[110:111]
	v_pk_mul_f32 v[96:97], v[4:5], v[108:109]
	v_pk_mul_f32 v[102:103], v[2:3], v[106:107]
	v_pk_mul_f32 v[100:101], v[0:1], v[104:105]
	v_pk_mul_f32 v[106:107], v[14:15], v[120:121]
	v_pk_mul_f32 v[104:105], v[12:13], v[118:119]
	v_pk_mul_f32 v[110:111], v[10:11], v[114:115]
	v_pk_mul_f32 v[108:109], v[8:9], v[122:123]
	global_store_dwordx4 v[116:117], v[96:99], off
	global_store_dwordx4 v[116:117], v[100:103], off offset:16
	global_store_dwordx4 v[116:117], v[104:107], off offset:512
	global_store_dwordx4 v[116:117], v[108:111], off offset:528
	v_lshlrev_b64 v[98:99], 12, v[210:211]
	v_lshl_add_u64 v[98:99], s[20:21], 0, v[98:99]
	v_lshl_add_u64 v[98:99], v[98:99], 0, v[144:145]
	s_waitcnt vmcnt(13)
	v_fmamk_f32 v96, v247, 0x3a800000, v226
	v_rsq_f32_e32 v96, v96
	s_nop 0
	v_pk_mul_f32 v[92:93], v[92:93], v[96:97] op_sel_hi:[1,0]
	v_pk_mul_f32 v[94:95], v[94:95], v[96:97] op_sel_hi:[1,0]
	v_pk_mul_f32 v[88:89], v[88:89], v[96:97] op_sel_hi:[1,0]
	v_pk_mul_f32 v[90:91], v[90:91], v[96:97] op_sel_hi:[1,0]
	v_pk_mul_f32 v[100:101], v[84:85], v[96:97] op_sel_hi:[1,0]
	v_pk_mul_f32 v[102:103], v[86:87], v[96:97] op_sel_hi:[1,0]
	v_pk_mul_f32 v[104:105], v[80:81], v[96:97] op_sel_hi:[1,0]
	v_pk_mul_f32 v[96:97], v[82:83], v[96:97] op_sel_hi:[1,0]
	v_pk_mul_f32 v[82:83], v[6:7], v[94:95]
	v_pk_mul_f32 v[80:81], v[4:5], v[92:93]
	v_pk_mul_f32 v[86:87], v[2:3], v[90:91]
	v_pk_mul_f32 v[84:85], v[0:1], v[88:89]
	v_pk_mul_f32 v[90:91], v[14:15], v[102:103]
	v_pk_mul_f32 v[88:89], v[12:13], v[100:101]
	v_pk_mul_f32 v[94:95], v[10:11], v[96:97]
	v_pk_mul_f32 v[92:93], v[8:9], v[104:105]
	global_store_dwordx4 v[98:99], v[80:83], off
	global_store_dwordx4 v[98:99], v[84:87], off offset:16
	global_store_dwordx4 v[98:99], v[88:91], off offset:512
	global_store_dwordx4 v[98:99], v[92:95], off offset:528
	v_lshlrev_b64 v[82:83], 12, v[208:209]
	v_lshl_add_u64 v[82:83], s[20:21], 0, v[82:83]
	v_lshl_add_u64 v[82:83], v[82:83], 0, v[144:145]
	s_waitcnt vmcnt(16)
	v_fmamk_f32 v80, v248, 0x3a800000, v226
	v_rsq_f32_e32 v80, v80
	s_nop 0
	v_pk_mul_f32 v[76:77], v[76:77], v[80:81] op_sel_hi:[1,0]
	v_pk_mul_f32 v[78:79], v[78:79], v[80:81] op_sel_hi:[1,0]
	v_pk_mul_f32 v[72:73], v[72:73], v[80:81] op_sel_hi:[1,0]
	v_pk_mul_f32 v[74:75], v[74:75], v[80:81] op_sel_hi:[1,0]
	v_pk_mul_f32 v[84:85], v[68:69], v[80:81] op_sel_hi:[1,0]
	v_pk_mul_f32 v[86:87], v[70:71], v[80:81] op_sel_hi:[1,0]
	v_pk_mul_f32 v[88:89], v[64:65], v[80:81] op_sel_hi:[1,0]
	v_pk_mul_f32 v[80:81], v[66:67], v[80:81] op_sel_hi:[1,0]
	v_pk_mul_f32 v[66:67], v[6:7], v[78:79]
	v_pk_mul_f32 v[64:65], v[4:5], v[76:77]
	v_pk_mul_f32 v[70:71], v[2:3], v[74:75]
	v_pk_mul_f32 v[68:69], v[0:1], v[72:73]
	v_pk_mul_f32 v[74:75], v[14:15], v[86:87]
	v_pk_mul_f32 v[72:73], v[12:13], v[84:85]
	v_pk_mul_f32 v[78:79], v[10:11], v[80:81]
	v_pk_mul_f32 v[76:77], v[8:9], v[88:89]
	global_store_dwordx4 v[82:83], v[64:67], off
	global_store_dwordx4 v[82:83], v[68:71], off offset:16
	global_store_dwordx4 v[82:83], v[72:75], off offset:512
	global_store_dwordx4 v[82:83], v[76:79], off offset:528
	v_lshlrev_b64 v[66:67], 12, v[206:207]
	v_lshl_add_u64 v[66:67], s[20:21], 0, v[66:67]
	v_lshl_add_u64 v[66:67], v[66:67], 0, v[144:145]
	s_waitcnt vmcnt(19)
	v_fmamk_f32 v64, v249, 0x3a800000, v226
	v_rsq_f32_e32 v64, v64
	s_nop 0
	v_pk_mul_f32 v[60:61], v[60:61], v[64:65] op_sel_hi:[1,0]
	v_pk_mul_f32 v[62:63], v[62:63], v[64:65] op_sel_hi:[1,0]
	v_pk_mul_f32 v[56:57], v[56:57], v[64:65] op_sel_hi:[1,0]
	v_pk_mul_f32 v[58:59], v[58:59], v[64:65] op_sel_hi:[1,0]
	v_pk_mul_f32 v[68:69], v[52:53], v[64:65] op_sel_hi:[1,0]
	v_pk_mul_f32 v[70:71], v[54:55], v[64:65] op_sel_hi:[1,0]
	v_pk_mul_f32 v[72:73], v[48:49], v[64:65] op_sel_hi:[1,0]
	v_pk_mul_f32 v[64:65], v[50:51], v[64:65] op_sel_hi:[1,0]
	v_pk_mul_f32 v[50:51], v[6:7], v[62:63]
	v_pk_mul_f32 v[48:49], v[4:5], v[60:61]
	v_pk_mul_f32 v[54:55], v[2:3], v[58:59]
	v_pk_mul_f32 v[52:53], v[0:1], v[56:57]
	v_pk_mul_f32 v[58:59], v[14:15], v[70:71]
	v_pk_mul_f32 v[56:57], v[12:13], v[68:69]
	v_pk_mul_f32 v[62:63], v[10:11], v[64:65]
	v_pk_mul_f32 v[60:61], v[8:9], v[72:73]
	global_store_dwordx4 v[66:67], v[48:51], off
	global_store_dwordx4 v[66:67], v[52:55], off offset:16
	global_store_dwordx4 v[66:67], v[56:59], off offset:512
	global_store_dwordx4 v[66:67], v[60:63], off offset:528
	v_lshlrev_b64 v[50:51], 12, v[204:205]
	v_lshl_add_u64 v[50:51], s[20:21], 0, v[50:51]
	v_lshl_add_u64 v[50:51], v[50:51], 0, v[144:145]
	s_waitcnt vmcnt(22)
	v_fmamk_f32 v48, v250, 0x3a800000, v226
	v_rsq_f32_e32 v48, v48
	s_nop 0
	v_pk_mul_f32 v[44:45], v[44:45], v[48:49] op_sel_hi:[1,0]
	v_pk_mul_f32 v[46:47], v[46:47], v[48:49] op_sel_hi:[1,0]
	v_pk_mul_f32 v[40:41], v[40:41], v[48:49] op_sel_hi:[1,0]
	v_pk_mul_f32 v[42:43], v[42:43], v[48:49] op_sel_hi:[1,0]
	v_pk_mul_f32 v[52:53], v[36:37], v[48:49] op_sel_hi:[1,0]
	v_pk_mul_f32 v[54:55], v[38:39], v[48:49] op_sel_hi:[1,0]
	v_pk_mul_f32 v[56:57], v[32:33], v[48:49] op_sel_hi:[1,0]
	v_pk_mul_f32 v[48:49], v[34:35], v[48:49] op_sel_hi:[1,0]
	v_pk_mul_f32 v[34:35], v[6:7], v[46:47]
	v_pk_mul_f32 v[32:33], v[4:5], v[44:45]
	v_pk_mul_f32 v[38:39], v[2:3], v[42:43]
	v_pk_mul_f32 v[36:37], v[0:1], v[40:41]
	v_pk_mul_f32 v[42:43], v[14:15], v[54:55]
	v_pk_mul_f32 v[40:41], v[12:13], v[52:53]
	v_pk_mul_f32 v[46:47], v[10:11], v[48:49]
	v_pk_mul_f32 v[44:45], v[8:9], v[56:57]
	global_store_dwordx4 v[50:51], v[32:35], off
	global_store_dwordx4 v[50:51], v[36:39], off offset:16
	global_store_dwordx4 v[50:51], v[40:43], off offset:512
	global_store_dwordx4 v[50:51], v[44:47], off offset:528
	v_lshlrev_b64 v[34:35], 12, v[202:203]
	v_lshl_add_u64 v[34:35], s[20:21], 0, v[34:35]
	v_lshl_add_u64 v[40:41], v[34:35], 0, v[144:145]
	s_waitcnt vmcnt(25)
	v_fmamk_f32 v32, v251, 0x3a800000, v226
	v_rsq_f32_e32 v32, v32
	s_nop 0
	v_pk_mul_f32 v[28:29], v[28:29], v[32:33] op_sel_hi:[1,0]
	v_pk_mul_f32 v[30:31], v[30:31], v[32:33] op_sel_hi:[1,0]
	v_pk_mul_f32 v[34:35], v[24:25], v[32:33] op_sel_hi:[1,0]
	v_pk_mul_f32 v[36:37], v[26:27], v[32:33] op_sel_hi:[1,0]
	v_pk_mul_f32 v[38:39], v[140:141], v[32:33] op_sel_hi:[1,0]
	v_pk_mul_f32 v[42:43], v[142:143], v[32:33] op_sel_hi:[1,0]
	v_pk_mul_f32 v[44:45], v[136:137], v[32:33] op_sel_hi:[1,0]
	v_pk_mul_f32 v[46:47], v[138:139], v[32:33] op_sel_hi:[1,0]
	v_pk_mul_f32 v[26:27], v[6:7], v[30:31]
	v_pk_mul_f32 v[24:25], v[4:5], v[28:29]
	v_pk_mul_f32 v[30:31], v[2:3], v[36:37]
	v_pk_mul_f32 v[28:29], v[0:1], v[34:35]
	v_pk_mul_f32 v[34:35], v[14:15], v[42:43]
	v_pk_mul_f32 v[32:33], v[12:13], v[38:39]
	v_pk_mul_f32 v[38:39], v[10:11], v[46:47]
	v_pk_mul_f32 v[36:37], v[8:9], v[44:45]
	global_store_dwordx4 v[40:41], v[24:27], off
	global_store_dwordx4 v[40:41], v[28:31], off offset:16
	global_store_dwordx4 v[40:41], v[32:35], off offset:512
	global_store_dwordx4 v[40:41], v[36:39], off offset:528
	v_lshlrev_b64 v[24:25], 12, v[200:201]
	v_lshl_add_u64 v[24:25], s[20:21], 0, v[24:25]
	v_lshl_add_u64 v[24:25], v[24:25], 0, v[144:145]
	s_waitcnt vmcnt(28)
	v_fmamk_f32 v26, v252, 0x3a800000, v226
	v_rsq_f32_e32 v26, v26
	s_nop 0
	v_pk_mul_f32 v[16:17], v[16:17], v[26:27] op_sel_hi:[1,0]
	v_pk_mul_f32 v[18:19], v[18:19], v[26:27] op_sel_hi:[1,0]
	v_pk_mul_f32 v[20:21], v[20:21], v[26:27] op_sel_hi:[1,0]
	v_pk_mul_f32 v[22:23], v[22:23], v[26:27] op_sel_hi:[1,0]
	v_pk_mul_f32 v[28:29], v[132:133], v[26:27] op_sel_hi:[1,0]
	v_pk_mul_f32 v[30:31], v[128:129], v[26:27] op_sel_hi:[1,0]
	v_pk_mul_f32 v[32:33], v[134:135], v[26:27] op_sel_hi:[1,0]
	v_pk_mul_f32 v[26:27], v[130:131], v[26:27] op_sel_hi:[1,0]
	v_pk_mul_f32 v[6:7], v[6:7], v[18:19]
	v_pk_mul_f32 v[4:5], v[4:5], v[16:17]
	v_pk_mul_f32 v[2:3], v[2:3], v[22:23]
	v_pk_mul_f32 v[0:1], v[0:1], v[20:21]
	v_pk_mul_f32 v[14:15], v[14:15], v[30:31]
	v_pk_mul_f32 v[12:13], v[12:13], v[28:29]
	v_pk_mul_f32 v[10:11], v[10:11], v[26:27]
	v_pk_mul_f32 v[8:9], v[8:9], v[32:33]
	global_store_dwordx4 v[24:25], v[4:7], off
	global_store_dwordx4 v[24:25], v[0:3], off offset:16
	global_store_dwordx4 v[24:25], v[12:15], off offset:512
	global_store_dwordx4 v[24:25], v[8:11], off offset:528
	s_cbranch_vccnz .LBB0_887
	s_andn2_b64 vcc, exec, s[36:37]
	s_cbranch_vccnz .LBB0_886
	s_barrier
	s_branch .LBB0_886
